# work queues: first ticket of each workgroup is static (its own index), later tickets nb + counter; avoids 256-way contended atomic at phase start
# speedup vs baseline: 1.2022x; 1.0043x over previous
.LBB0_336:
	v_readlane_b32 s4, v236, 39
	v_readlane_b32 s5, v236, 40
	s_barrier
	s_and_saveexec_b64 s[38:39], s[4:5]
	s_cbranch_execz .LBB0_340
	s_mov_b64 s[42:43], exec
	v_mbcnt_lo_u32_b32 v0, s42, 0
	v_mbcnt_hi_u32_b32 v0, s43, v0
	v_cmp_eq_u32_e32 vcc, 0, v0
	s_and_saveexec_b64 s[40:41], vcc
	s_cbranch_execz .LBB0_339
	s_bcnt1_i32_b64 s35, s[42:43]
	v_readlane_b32 s4, v235, 56
	v_mov_b32_e32 v1, s35
	v_readlane_b32 s5, v235, 57
	s_nop 4
	v_readlane_b32 s99, v237, 0
	s_nop 1
	v_mov_b32_e32 v1, s99

.LBB0_342:
	s_or_b64 exec, exec, s[40:41]
	s_waitcnt vmcnt(0)
	v_readfirstlane_b32 s40, v1
	s_nop 1
	v_add_u32_e32 v0, s40, v0
	v_readlane_b32 s99, v235, 55
	s_nop 1
	v_add_u32_e32 v0, s99, v0
	ds_write_b32 v208, v0

.LBB0_561:
	s_andn2_b64 vcc, exec, s[38:39]
	s_cbranch_vccnz .LBB0_763
	v_readlane_b32 s4, v235, 63
	s_cmp_lt_i32 s4, 2
	s_mov_b64 s[38:39], -1
	s_cbranch_scc1 .LBB0_705
	s_lshl_b32 s62, s36, 5
	s_lshl_b32 s18, s36, 4
	v_readlane_b32 s4, v235, 63
	s_cmp_gt_i32 s4, 2
	s_cbranch_scc0 .LBB0_637
	v_readlane_b32 s4, v236, 39
	v_readlane_b32 s5, v236, 40
	s_barrier
	s_and_saveexec_b64 s[38:39], s[4:5]
	s_movk_i32 s13, 0x53f
	s_cbranch_execz .LBB0_568
	s_mov_b64 s[42:43], exec
	v_mbcnt_lo_u32_b32 v0, s42, 0
	v_mbcnt_hi_u32_b32 v0, s43, v0
	v_cmp_eq_u32_e32 vcc, 0, v0
	s_and_saveexec_b64 s[40:41], vcc
	s_cbranch_execz .LBB0_567
	s_bcnt1_i32_b64 s35, s[42:43]
	v_readlane_b32 s4, v235, 56
	v_mov_b32_e32 v1, s35
	v_readlane_b32 s5, v235, 57
	s_nop 4
	v_readlane_b32 s99, v237, 0
	s_nop 1
	v_mov_b32_e32 v1, s99

.LBB0_570:
	s_or_b64 exec, exec, s[40:41]
	s_waitcnt vmcnt(0)
	v_readfirstlane_b32 s35, v1
	s_nop 1
	v_add_u32_e32 v0, s35, v0
	v_readlane_b32 s99, v235, 55
	s_nop 1
	v_add_u32_e32 v0, s99, v0
	ds_write_b32 v208, v0

.LBB0_637:
	s_and_b64 vcc, exec, s[38:39]
	s_cbranch_vccz .LBB0_704
	v_readlane_b32 s4, v236, 39
	v_readlane_b32 s5, v236, 40
	s_barrier
	s_and_saveexec_b64 s[38:39], s[4:5]
	s_cbranch_execz .LBB0_642
	s_mov_b64 s[42:43], exec
	v_mbcnt_lo_u32_b32 v0, s42, 0
	v_mbcnt_hi_u32_b32 v0, s43, v0
	v_cmp_eq_u32_e32 vcc, 0, v0
	s_and_saveexec_b64 s[40:41], vcc
	s_cbranch_execz .LBB0_641
	s_bcnt1_i32_b64 s35, s[42:43]
	v_readlane_b32 s4, v235, 56
	v_mov_b32_e32 v1, s35
	v_readlane_b32 s5, v235, 57
	s_nop 4
	v_readlane_b32 s99, v237, 0
	s_nop 1
	v_mov_b32_e32 v1, s99

.LBB0_644:
	s_or_b64 exec, exec, s[46:47]
	s_waitcnt vmcnt(0)
	v_readfirstlane_b32 s35, v1
	s_nop 1
	v_add_u32_e32 v0, s35, v0
	v_readlane_b32 s99, v235, 55
	s_nop 1
	v_add_u32_e32 v0, s99, v0
	ds_write_b32 v208, v0
